# v36 + weight-conversion split point moved from item 9216 to 10240 (1024 items fewer for the in-proj idle workgroups, more in P4)
# baseline (speedup 1.0000x reference)
; #define LAS __attribute__((address_space(3)))
; template <class Resolve>
; DI void p0_convert(const Resolve R, int first, int stride, int total, LAS float* scr, int lane) {
;     for (int it = first; it < total; it += 2 * stride) {
;         const bool two = it + stride < total;
; __global__ void __launch_bounds__(512, 2) fwd_kernel(Args a) {
;     ...
;             constexpr int NT = (MP / 256) * (INW / 256); const int rounds = (NT + G - 1) / G, first_idle = NT - (rounds - 1) * G;
;             const int nidle = (first_idle < G) ? (G - first_idle) : G, me = (first_idle < G) ? (bx - first_idle) : bx;
;             if (me >= 0) {
;                 LAS float* scr = (LAS float*)(lds + wid * 17408);
;                 constexpr int I_OUT = (DM / 64) * (DM / 32), I_UP = (DM / 64) * (FF / 32), I_DN = (FF / 64) * (DM / 32);
;                 p0_convert(ResRest{w_out, w_up, w_dn, WOUT, WUP, WDN, ln2_g}, NP0_REST + me * 8 + wid, nidle * 8, I_OUT + I_UP + I_DN, scr, lane);
;             }
.LBB0_147:
	s_abs_i32 s0, s64
	v_cvt_f32_u32_e32 v0, s0
	s_sub_i32 s3, 0, s0
	s_add_i32 s1, s64, 0x2b4
	s_xor_b32 s2, s1, s64
	v_rcp_iflag_f32_e32 v0, v0
	s_abs_i32 s1, s1
	s_ashr_i32 s2, s2, 31
	v_mul_f32_e32 v0, 0x4f7ffffe, v0
	v_cvt_u32_f32_e32 v0, v0
	s_nop 0
	v_readfirstlane_b32 s4, v0
	s_mul_i32 s3, s3, s4
	s_mul_hi_u32 s3, s4, s3
	s_add_i32 s4, s4, s3
	s_mul_hi_u32 s3, s1, s4
	s_mul_i32 s4, s3, s0
	s_sub_i32 s1, s1, s4
	s_add_i32 s5, s3, 1
	s_sub_i32 s4, s1, s0
	s_cmp_ge_u32 s1, s0
	s_cselect_b32 s3, s5, s3
	s_cselect_b32 s1, s4, s1
	s_add_i32 s4, s3, 1
	s_cmp_ge_u32 s1, s0
	s_cselect_b32 s0, s4, s3
	s_xor_b32 s0, s0, s2
	s_not_b32 s1, s2
	s_add_i32 s0, s1, s0
	s_mul_i32 s0, s0, s64
	s_sub_i32 s0, 0x2b5, s0
	s_cmp_lt_i32 s0, s64
	s_cselect_b32 s0, s0, 0
	s_sub_i32 s1, s92, s0
	s_cmp_lt_i32 s1, 0
	s_cbranch_scc1 .LBB0_172
	s_lshl_b32 s1, s1, 3
	v_readlane_b32 s2, v254, 6
	s_add_i32 s1, s2, s1
	s_add_i32 s24, s1, 0x2800
	s_cmpk_gt_i32 s24, 0x47ff
	s_cbranch_scc1 .LBB0_172
	s_sub_i32 s1, s64, s0
	v_readlane_b32 s3, v254, 6
	s_lshl_b32 s25, s1, 4
	s_lshl_b32 s1, s0, 3
	s_mul_i32 s2, s3, 0x4400
	s_sub_i32 s26, 0, s1
	s_lshl_b32 s1, s92, 3
	s_add_i32 s2, s2, 0
	v_lshrrev_b32_e32 v72, 3, v152
	v_and_b32_e32 v0, 28, v153
	v_and_b32_e32 v1, 7, v253
	s_add_i32 s27, s3, s1
	s_lshl_b32 s1, s64, 3
	s_lshl_b32 s0, s0, 4
	v_mov_b32_e32 v65, 0
	v_lshl_add_u32 v3, v1, 4, s2
	v_mul_u32_u24_e32 v4, 0x84, v72
	v_lshlrev_b32_e32 v2, 3, v1
	v_mul_u32_u24_e32 v1, 0x420, v1
	v_lshlrev_b32_e32 v5, 2, v72
	s_sub_i32 s28, s1, s0
	v_lshlrev_b32_e32 v66, 2, v0
	v_or_b32_e32 v73, 8, v72
	v_or_b32_e32 v74, 16, v72
	v_or_b32_e32 v75, 24, v72
	v_add3_u32 v76, s2, v1, v5
	s_addk_i32 s28, 0x2800
	v_mov_b32_e32 v68, v66
	v_mov_b32_e32 v69, v65
	v_lshlrev_b32_e32 v64, 1, v2
	v_add_u32_e32 v77, v3, v4
	s_branch .LBB0_151
.LBB0_150:
	s_add_i32 s27, s27, s25
	s_add_i32 s0, s26, s27
	s_add_i32 s24, s24, s25
	s_addk_i32 s0, 0x2800
	s_cmpk_lt_i32 s0, 0x4800
	s_cbranch_scc0 .LBB0_172
.LBB0_151:
	s_add_i32 s2, s26, s27
	v_readlane_b32 s68, v254, 7
	s_add_i32 s4, s2, 0x2800
	v_readlane_b32 s74, v254, 13
	v_readlane_b32 s75, v254, 14
	s_movk_i32 s29, 0x800
	s_mov_b64 s[6:7], 0x800
	s_cmpk_lt_i32 s4, 0x800
	s_mov_b64 s[14:15], s[88:89]
	s_mov_b64 s[22:23], s[74:75]
	s_mov_b64 s[12:13], 0x800
	s_movk_i32 s19, 0x800
	s_mov_b32 s16, s24
	s_mov_b64 s[0:1], 0
	v_readlane_b32 s69, v254, 8
	v_readlane_b32 s70, v254, 9
	v_readlane_b32 s71, v254, 10
	v_readlane_b32 s72, v254, 11
	v_readlane_b32 s73, v254, 12
	v_readlane_b32 s76, v254, 15
	v_readlane_b32 s77, v254, 16
	v_readlane_b32 s78, v254, 17
	v_readlane_b32 s79, v254, 18
	v_readlane_b32 s80, v254, 19
	v_readlane_b32 s81, v254, 20
	v_readlane_b32 s82, v254, 21
	v_readlane_b32 s83, v254, 22
	s_cbranch_scc1 .LBB0_157
	s_cmpk_gt_u32 s4, 0x27ff
	s_cbranch_scc0 .LBB0_155
	v_readlane_b32 s68, v254, 7
	v_readlane_b32 s80, v254, 19
	v_readlane_b32 s81, v254, 20
	s_add_i32 s16, s2, 0
	v_readlane_b32 s69, v254, 8
	v_readlane_b32 s70, v254, 9
	v_readlane_b32 s71, v254, 10
	v_readlane_b32 s72, v254, 11
	v_readlane_b32 s73, v254, 12
	v_readlane_b32 s74, v254, 13
	v_readlane_b32 s75, v254, 14
	v_readlane_b32 s76, v254, 15
	v_readlane_b32 s77, v254, 16
	v_readlane_b32 s78, v254, 17
	v_readlane_b32 s79, v254, 18
	v_readlane_b32 s82, v254, 21
	v_readlane_b32 s83, v254, 22
	s_mov_b64 s[22:23], s[80:81]
	s_cbranch_execz .LBB0_156
	s_mov_b64 s[12:13], 0x2000
	s_mov_b64 s[14:15], s[84:85]
	s_branch .LBB0_157

; #define LAS __attribute__((address_space(3)))
; template <class Resolve>
; DI void p0_convert(const Resolve R, int first, int stride, int total, LAS float* scr, int lane) {
;     for (int it = first; it < total; it += 2 * stride) {
;         const bool two = it + stride < total;
;         const TItem t0 = R(it), t1 = R(two ? it + stride : it);
; __global__ void __launch_bounds__(512, 2) fwd_kernel(Args a) {
;     ...
;         {
;             LAS float* scr = (LAS float*)(lds + wid * 17408);
;             p0_convert(ResRest{w_out, w_up, w_dn, WOUT, WUP, WDN, ln2_g}, bx * 8 + wid, G * 8, NP0_REST, scr, lane);
;         }
.LBB0_437:
	s_lshl_b32 s0, s92, 3
	v_readlane_b32 s1, v254, 6
	s_add_i32 s20, s1, s0
	v_readlane_b32 s30, v254, 41
	s_cmpk_gt_i32 s20, 0x27ff
	v_readlane_b32 s31, v254, 42
	s_cbranch_scc1 .LBB0_457
	v_readlane_b32 s0, v254, 6
	s_mulk_i32 s0, 0x4400
	v_lshlrev_b32_e32 v0, 2, v253
	s_add_i32 s0, s0, 0
	v_lshrrev_b32_e32 v72, 3, v152
	v_and_b32_e32 v0, 28, v0
	v_and_b32_e32 v1, 7, v253
	v_mov_b32_e32 v65, 0
	v_lshl_add_u32 v3, v1, 4, s0
	v_mul_u32_u24_e32 v4, 0x84, v72
	v_lshlrev_b32_e32 v2, 3, v1
	v_mul_u32_u24_e32 v1, 0x420, v1
	v_lshlrev_b32_e32 v5, 2, v72
	v_lshlrev_b32_e32 v66, 2, v0
	s_lshl_b32 s21, s64, 3
	v_or_b32_e32 v73, 8, v72
	v_or_b32_e32 v74, 16, v72
	v_or_b32_e32 v75, 24, v72
	v_add3_u32 v76, s0, v1, v5
	s_lshl_b32 s22, s64, 4
	v_mov_b32_e32 v68, v66
	v_mov_b32_e32 v69, v65
	v_lshlrev_b32_e32 v64, 1, v2
	v_add_u32_e32 v77, v3, v4
	s_branch .LBB0_440
.LBB0_439:
	s_add_i32 s20, s20, s22
	s_cmpk_gt_i32 s20, 0x27ff
	s_cbranch_scc1 .LBB0_457

; #define LAS __attribute__((address_space(3)))
; template <class Resolve>
; DI void p0_convert(const Resolve R, int first, int stride, int total, LAS float* scr, int lane) {
;     for (int it = first; it < total; it += 2 * stride) {
;         const bool two = it + stride < total;
;         const TItem t0 = R(it), t1 = R(two ? it + stride : it);
.LBB0_442:
	s_add_i32 s4, s21, s20
	s_cmpk_lt_i32 s4, 0x2800
	s_cselect_b64 s[16:17], -1, 0
	s_and_b64 s[2:3], s[16:17], exec
	s_cselect_b32 s23, s4, s20
	s_cmpk_lt_i32 s23, 0x800
	s_cbranch_scc1 .LBB0_446
	s_cmpk_gt_u32 s23, 0x27ff
	s_cbranch_scc0 .LBB0_447
	v_readlane_b32 s68, v254, 7
	v_readlane_b32 s80, v254, 19
	v_readlane_b32 s81, v254, 20
	s_add_i32 s11, s23, 0xffffd800
	s_mov_b64 s[2:3], 0
	v_readlane_b32 s69, v254, 8
	v_readlane_b32 s70, v254, 9
	v_readlane_b32 s71, v254, 10
	v_readlane_b32 s72, v254, 11
	v_readlane_b32 s73, v254, 12
	v_readlane_b32 s74, v254, 13
	v_readlane_b32 s75, v254, 14
	v_readlane_b32 s76, v254, 15
	v_readlane_b32 s77, v254, 16
	v_readlane_b32 s78, v254, 17
	v_readlane_b32 s79, v254, 18
	v_readlane_b32 s82, v254, 21
	v_readlane_b32 s83, v254, 22
	s_mov_b64 s[14:15], s[80:81]
	s_cbranch_execz .LBB0_448
	s_mov_b64 s[4:5], 0x2000
	s_mov_b64 s[6:7], s[84:85]
	s_branch .LBB0_449
